# GEMM K-loop LDS-DMA addressing: scalar base + 32-bit lane offset instead of a 64-bit VALU add per load
# speedup vs baseline: 1.0006x; 1.0006x over previous
; #define PG8_STAGE(bufoff, gbase, voff) do { _Pragma("unroll") for (int _i = 0; _i < 2; ++_i) \
;         __builtin_amdgcn_global_load_lds((const unsigned*)((const char*)(gbase) + (voff)[_i]), (PG8_LAS unsigned*)(lds + (bufoff) + ldsw + _i * 8192), 16, 0, 0); } while (0)
; #define PG8_LDA(dst, b, h) do { _Pragma("unroll") for (int m = 0; m < 4; ++m) _Pragma("unroll") for (int k = 0; k < 2; ++k) dst[m][k] = *(const PG8_LAS bf16x8*)(lds + PG8_SA(b, h) + aoff + m * 2048 + k * 1024); } while (0)
; #define PG8_LDB(dst, b, h) do { _Pragma("unroll") for (int n = 0; n < 2; ++n) _Pragma("unroll") for (int k = 0; k < 2; ++k) dst[n][k] = *(const PG8_LAS bf16x8*)(lds + PG8_SB(b, h) + boff + n * 2048 + k * 1024); } while (0)
; #define PG8_WAIT_V(n) asm volatile("s_waitcnt vmcnt(" #n ")" ::: "memory")
; #define PG8_WAIT_L(n) asm volatile("s_waitcnt lgkmcnt(" #n ")" ::: "memory")
; #define PG8_BAR __builtin_amdgcn_s_barrier()
; #define PG8_SCHED __builtin_amdgcn_sched_barrier(0)
; template <class Epi, class Sched, bool ALIGN_EPI = false, bool SP2 = false>
; __device__ __forceinline__ void gemm_phase(PG8_LAS unsigned char* lds, const Gemm g, const Sched& S, const Epi& E) {
;     ...
;         const bool has_next = S.next(ui + 1, nxt);
;         const char* nA = has_next ? (const char*)g.A + (size_t)nxt.pm * tstep : cA; const char* nB = has_next ? (const char*)g.Bt + (size_t)nxt.pn * tstep : cB;
;         for (int t = 0; t < nt; t += 2) {
;             const bool last = (t == nt - 2);
;             const char* a1 = cA + (size_t)(t + 1) * kstepB;
;             const char* a2 = last ? nA : cA + (size_t)(t + 2) * kstepB; const char* b2 = last ? nB : cB + (size_t)(t + 2) * kstepB;
;             const char* a3 = a2 + kstepB; const char* b3 = b2 + kstepB;
;             if (last && has_next) S.a_ready(nxt);
;             if constexpr (SP2) {
;             PG8_LDB(B0, 0, 0); PG8_LDB(B1, 0, 1); PG8_SCHED; PG8_LDA(At, 0, 0); PG8_STAGE(PG8_SA(1, 1), a1 + hstepB, voffA);
;             PG8_WAIT_V(8); PG8_WAIT_L(0); PG8_BAR; PG8_MMA(0, 0, At, B0); PG8_MMA(0, 1, At, B1); PG8_BAR; PG8_SCHED;
;             PG8_LDA(At, 0, 1); PG8_STAGE(PG8_SB(0, 0), b2, voffB); PG8_STAGE(PG8_SB(0, 1), b2 + hstepB, voffB); PG8_STAGE(PG8_SA(0, 0), a2, voffA);
;             PG8_WAIT_V(8); PG8_WAIT_L(0); PG8_BAR; PG8_MMA(1, 0, At, B0); PG8_MMA(1, 1, At, B1); PG8_BAR; PG8_SCHED;
.LBB0_193:
	s_add_i32 s84, s38, 2
	s_add_u32 s39, s36, 0x4000
	s_addc_u32 s40, s37, 0
	s_cmp_eq_u32 s31, s38
	s_cselect_b32 s42, s8, s39
	s_cselect_b32 s43, s9, s40
	s_cselect_b32 s40, s62, s78
	s_cselect_b32 s41, s63, s82
	s_add_u32 s38, s42, 0x8000
	s_addc_u32 s39, s43, 0
	s_add_i32 s90, 0, 0x10000
	s_add_i32 s64, 0, 0x14000
	v_add_u32_e32 v140, s90, v174
	v_add_u32_e32 v161, s64, v174
	ds_read_b128 v[128:131], v140
	ds_read_b128 v[132:135], v140 offset:1024
	ds_read_b128 v[136:139], v140 offset:2048
	ds_read_b128 v[140:143], v140 offset:3072
	ds_read_b128 v[144:147], v161
	ds_read_b128 v[148:151], v161 offset:1024
	ds_read_b128 v[178:181], v161 offset:2048
	ds_read_b128 v[182:185], v161 offset:3072
	s_add_i32 m0, s21, 0xc000
	ds_read_b128 v[186:189], v177
	ds_read_b128 v[190:193], v177 offset:1024
	ds_read_b128 v[194:197], v177 offset:2048
	ds_read_b128 v[198:201], v177 offset:3072
	ds_read_b128 v[202:205], v177 offset:4096
	ds_read_b128 v[206:209], v177 offset:5120
	ds_read_b128 v[210:213], v177 offset:6144
	ds_read_b128 v[214:217], v177 offset:7168
	global_load_lds_dwordx4 v168, s[36:37]
	s_add_i32 m0, s21, 0xe000
	s_nop 0
	global_load_lds_dwordx4 v170, s[36:37]
	s_waitcnt vmcnt(8)
	s_waitcnt lgkmcnt(0)
	s_barrier
	s_setprio 1
	s_waitcnt lgkmcnt(0)
	v_mfma_f32_16x16x32_bf16 v[124:127], v[128:131], v[186:189], v[124:127]
	v_mfma_f32_16x16x32_bf16 v[124:127], v[132:135], v[190:193], v[124:127]
	v_mfma_f32_16x16x32_bf16 v[120:123], v[136:139], v[186:189], v[120:123]
	v_mfma_f32_16x16x32_bf16 v[120:123], v[140:143], v[190:193], v[120:123]
	v_mfma_f32_16x16x32_bf16 v[108:111], v[128:131], v[194:197], v[108:111]
	v_mfma_f32_16x16x32_bf16 v[108:111], v[132:135], v[198:201], v[108:111]
	v_mfma_f32_16x16x32_bf16 v[104:107], v[136:139], v[194:197], v[104:107]
	v_mfma_f32_16x16x32_bf16 v[104:107], v[140:143], v[198:201], v[104:107]
	v_mfma_f32_16x16x32_bf16 v[92:95], v[128:131], v[202:205], v[92:95]
	v_mfma_f32_16x16x32_bf16 v[92:95], v[132:135], v[206:209], v[92:95]
	v_mfma_f32_16x16x32_bf16 v[88:91], v[136:139], v[202:205], v[88:91]
	v_mfma_f32_16x16x32_bf16 v[88:91], v[140:143], v[206:209], v[88:91]
	v_mfma_f32_16x16x32_bf16 v[76:79], v[128:131], v[210:213], v[76:79]
	v_mfma_f32_16x16x32_bf16 v[76:79], v[132:135], v[214:217], v[76:79]
	v_mfma_f32_16x16x32_bf16 v[72:75], v[136:139], v[210:213], v[72:75]
	v_mfma_f32_16x16x32_bf16 v[72:75], v[140:143], v[214:217], v[72:75]
	s_setprio 0
	s_setprio 1
	v_mfma_f32_16x16x32_bf16 v[116:119], v[144:147], v[186:189], v[116:119]
	v_mfma_f32_16x16x32_bf16 v[116:119], v[148:151], v[190:193], v[116:119]
	v_mfma_f32_16x16x32_bf16 v[112:115], v[178:181], v[186:189], v[112:115]
	v_mfma_f32_16x16x32_bf16 v[112:115], v[182:185], v[190:193], v[112:115]
	v_mfma_f32_16x16x32_bf16 v[100:103], v[144:147], v[194:197], v[100:103]
	v_mfma_f32_16x16x32_bf16 v[100:103], v[148:151], v[198:201], v[100:103]
	v_mfma_f32_16x16x32_bf16 v[96:99], v[178:181], v[194:197], v[96:99]
	v_mfma_f32_16x16x32_bf16 v[96:99], v[182:185], v[198:201], v[96:99]
	v_mfma_f32_16x16x32_bf16 v[84:87], v[144:147], v[202:205], v[84:87]
	v_mfma_f32_16x16x32_bf16 v[84:87], v[148:151], v[206:209], v[84:87]
	v_mfma_f32_16x16x32_bf16 v[80:83], v[178:181], v[202:205], v[80:83]
	v_mfma_f32_16x16x32_bf16 v[80:83], v[182:185], v[206:209], v[80:83]
	v_mfma_f32_16x16x32_bf16 v[68:71], v[144:147], v[210:213], v[68:71]
	v_mfma_f32_16x16x32_bf16 v[68:71], v[148:151], v[214:217], v[68:71]
	v_mfma_f32_16x16x32_bf16 v[64:67], v[178:181], v[210:213], v[64:67]
	v_mfma_f32_16x16x32_bf16 v[64:67], v[182:185], v[214:217], v[64:67]
	s_setprio 0
	s_barrier
	s_add_i32 s65, s90, s20
	s_mov_b32 m0, s65
	ds_read_b128 v[186:189], v177 offset:16384
	ds_read_b128 v[190:193], v177 offset:17408
	ds_read_b128 v[194:197], v177 offset:18432
	ds_read_b128 v[198:201], v177 offset:19456
	ds_read_b128 v[202:205], v177 offset:20480
	ds_read_b128 v[206:209], v177 offset:21504
	ds_read_b128 v[210:213], v177 offset:22528
	ds_read_b128 v[214:217], v177 offset:23552
	global_load_lds_dwordx4 v156, s[40:41]
	s_add_i32 m0, s65, 0x2000
	s_add_u32 vcc_lo, s40, 0x4000
	s_addc_u32 vcc_hi, s41, 0
	s_add_i32 s64, s64, s20
	global_load_lds_dwordx4 v152, s[40:41]
	s_mov_b32 m0, s64
	s_nop 0
	global_load_lds_dwordx4 v156, vcc
	s_add_i32 m0, s64, 0x2000
	s_nop 0
	global_load_lds_dwordx4 v152, vcc
	s_mov_b32 m0, s21
	s_nop 0
	global_load_lds_dwordx4 v158, s[42:43]
	s_mov_b32 m0, s22
	s_nop 0
	global_load_lds_dwordx4 v154, s[42:43]
	s_waitcnt vmcnt(8)
	s_waitcnt lgkmcnt(0)
	s_barrier
	s_setprio 1
	s_waitcnt lgkmcnt(0)
	v_mfma_f32_16x16x32_bf16 v[60:63], v[128:131], v[186:189], v[60:63]
	v_mfma_f32_16x16x32_bf16 v[60:63], v[132:135], v[190:193], v[60:63]
	v_mfma_f32_16x16x32_bf16 v[56:59], v[136:139], v[186:189], v[56:59]
	v_mfma_f32_16x16x32_bf16 v[56:59], v[140:143], v[190:193], v[56:59]
	v_mfma_f32_16x16x32_bf16 v[44:47], v[128:131], v[194:197], v[44:47]
	v_mfma_f32_16x16x32_bf16 v[44:47], v[132:135], v[198:201], v[44:47]
	v_mfma_f32_16x16x32_bf16 v[40:43], v[136:139], v[194:197], v[40:43]
	v_mfma_f32_16x16x32_bf16 v[40:43], v[140:143], v[198:201], v[40:43]
	v_mfma_f32_16x16x32_bf16 v[28:31], v[128:131], v[202:205], v[28:31]
	v_mfma_f32_16x16x32_bf16 v[28:31], v[132:135], v[206:209], v[28:31]
	v_mfma_f32_16x16x32_bf16 v[24:27], v[136:139], v[202:205], v[24:27]
	v_mfma_f32_16x16x32_bf16 v[24:27], v[140:143], v[206:209], v[24:27]
	v_mfma_f32_16x16x32_bf16 v[12:15], v[128:131], v[210:213], v[12:15]
	v_mfma_f32_16x16x32_bf16 v[12:15], v[132:135], v[214:217], v[12:15]
	v_mfma_f32_16x16x32_bf16 v[8:11], v[136:139], v[210:213], v[8:11]
	v_mfma_f32_16x16x32_bf16 v[8:11], v[140:143], v[214:217], v[8:11]
	s_setprio 0
	s_setprio 1
	v_mfma_f32_16x16x32_bf16 v[52:55], v[144:147], v[186:189], v[52:55]
	v_mfma_f32_16x16x32_bf16 v[52:55], v[148:151], v[190:193], v[52:55]
	v_mfma_f32_16x16x32_bf16 v[48:51], v[178:181], v[186:189], v[48:51]
	v_mfma_f32_16x16x32_bf16 v[48:51], v[182:185], v[190:193], v[48:51]
	v_mfma_f32_16x16x32_bf16 v[36:39], v[144:147], v[194:197], v[36:39]
	v_mfma_f32_16x16x32_bf16 v[36:39], v[148:151], v[198:201], v[36:39]
	v_mfma_f32_16x16x32_bf16 v[32:35], v[178:181], v[194:197], v[32:35]
	v_mfma_f32_16x16x32_bf16 v[32:35], v[182:185], v[198:201], v[32:35]
	v_mfma_f32_16x16x32_bf16 v[20:23], v[144:147], v[202:205], v[20:23]
	v_mfma_f32_16x16x32_bf16 v[20:23], v[148:151], v[206:209], v[20:23]
	v_mfma_f32_16x16x32_bf16 v[16:19], v[178:181], v[202:205], v[16:19]
	v_mfma_f32_16x16x32_bf16 v[16:19], v[182:185], v[206:209], v[16:19]
	v_mfma_f32_16x16x32_bf16 v[4:7], v[144:147], v[210:213], v[4:7]
	v_mfma_f32_16x16x32_bf16 v[4:7], v[148:151], v[214:217], v[4:7]
	v_mfma_f32_16x16x32_bf16 v[0:3], v[178:181], v[210:213], v[0:3]
	v_mfma_f32_16x16x32_bf16 v[0:3], v[182:185], v[214:217], v[0:3]
	s_setprio 0
	s_barrier
; #define PG8_STAGE(bufoff, gbase, voff) do { _Pragma("unroll") for (int _i = 0; _i < 2; ++_i) \
;         __builtin_amdgcn_global_load_lds((const unsigned*)((const char*)(gbase) + (voff)[_i]), (PG8_LAS unsigned*)(lds + (bufoff) + ldsw + _i * 8192), 16, 0, 0); } while (0)
; #define PG8_LDA(dst, b, h) do { _Pragma("unroll") for (int m = 0; m < 4; ++m) _Pragma("unroll") for (int k = 0; k < 2; ++k) dst[m][k] = *(const PG8_LAS bf16x8*)(lds + PG8_SA(b, h) + aoff + m * 2048 + k * 1024); } while (0)
; #define PG8_LDB(dst, b, h) do { _Pragma("unroll") for (int n = 0; n < 2; ++n) _Pragma("unroll") for (int k = 0; k < 2; ++k) dst[n][k] = *(const PG8_LAS bf16x8*)(lds + PG8_SB(b, h) + boff + n * 2048 + k * 1024); } while (0)
; #define PG8_MMA(ai, bj, At, Bt) do { __builtin_amdgcn_s_setprio(1); _Pragma("unroll") for (int m = 0; m < 4; ++m) _Pragma("unroll") for (int n = 0; n < 2; ++n) _Pragma("unroll") for (int k = 0; k < 2; ++k) \
;         acc[ai][bj][m][n] = __builtin_amdgcn_mfma_f32_16x16x32_bf16(Bt[n][k], At[m][k], acc[ai][bj][m][n], 0, 0, 0); __builtin_amdgcn_s_setprio(0); } while (0)
; #define PG8_WAIT_V(n) asm volatile("s_waitcnt vmcnt(" #n ")" ::: "memory")
; #define PG8_WAIT_L(n) asm volatile("s_waitcnt lgkmcnt(" #n ")" ::: "memory")
; #define PG8_BAR __builtin_amdgcn_s_barrier()
; #define PG8_SCHED __builtin_amdgcn_sched_barrier(0)
; template <class Epi, class Sched, bool ALIGN_EPI = false, bool SP2 = false>
; __device__ __forceinline__ void gemm_phase(PG8_LAS unsigned char* lds, const Gemm g, const Sched& S, const Epi& E) {
;     ...
;         for (int t = 0; t < nt; t += 2) {
;     ...
;             PG8_LDB(B0, 1, 0); PG8_LDB(B1, 1, 1); PG8_SCHED; PG8_LDA(At, 1, 0); PG8_STAGE(PG8_SA(0, 1), a2 + hstepB, voffA);
;             PG8_WAIT_V(8); PG8_WAIT_L(0); PG8_BAR; PG8_MMA(0, 0, At, B0); PG8_MMA(0, 1, At, B1); PG8_BAR; PG8_SCHED;
;             PG8_LDA(At, 1, 1); PG8_STAGE(PG8_SB(1, 0), b3, voffB); PG8_STAGE(PG8_SB(1, 1), b3 + hstepB, voffB); PG8_STAGE(PG8_SA(1, 0), a3, voffA);
;             PG8_WAIT_V(8); PG8_WAIT_L(0); PG8_BAR; PG8_MMA(1, 0, At, B0); PG8_MMA(1, 1, At, B1); PG8_BAR; PG8_SCHED;
	s_add_i32 s64, 0, 0x18000
	s_add_i32 s65, 0, 0x1c000
	v_add_u32_e32 v140, s64, v174
	v_add_u32_e32 v161, s65, v174
	ds_read_b128 v[128:131], v140
	ds_read_b128 v[132:135], v140 offset:1024
	ds_read_b128 v[136:139], v140 offset:2048
	ds_read_b128 v[140:143], v140 offset:3072
	ds_read_b128 v[144:147], v161
	ds_read_b128 v[148:151], v161 offset:1024
	ds_read_b128 v[178:181], v161 offset:2048
	ds_read_b128 v[182:185], v161 offset:3072
	s_add_u32 s42, s42, 0x4000
	s_addc_u32 s43, s43, 0
	s_mov_b32 m0, s23
	ds_read_b128 v[186:189], v177 offset:32768
	ds_read_b128 v[190:193], v177 offset:33792
	ds_read_b128 v[194:197], v177 offset:34816
	ds_read_b128 v[198:201], v177 offset:35840
	ds_read_b128 v[202:205], v177 offset:36864
	ds_read_b128 v[206:209], v177 offset:37888
	ds_read_b128 v[210:213], v177 offset:38912
	ds_read_b128 v[214:217], v177 offset:39936
	global_load_lds_dwordx4 v158, s[42:43]
	s_mov_b32 m0, s24
	s_nop 0
	global_load_lds_dwordx4 v154, s[42:43]
	s_waitcnt vmcnt(8)
	s_waitcnt lgkmcnt(0)
	s_barrier
	s_setprio 1
	s_waitcnt lgkmcnt(0)
	v_mfma_f32_16x16x32_bf16 v[124:127], v[128:131], v[186:189], v[124:127]
	v_mfma_f32_16x16x32_bf16 v[124:127], v[132:135], v[190:193], v[124:127]
	v_mfma_f32_16x16x32_bf16 v[120:123], v[136:139], v[186:189], v[120:123]
	v_mfma_f32_16x16x32_bf16 v[120:123], v[140:143], v[190:193], v[120:123]
	v_mfma_f32_16x16x32_bf16 v[108:111], v[128:131], v[194:197], v[108:111]
	v_mfma_f32_16x16x32_bf16 v[108:111], v[132:135], v[198:201], v[108:111]
	v_mfma_f32_16x16x32_bf16 v[104:107], v[136:139], v[194:197], v[104:107]
	v_mfma_f32_16x16x32_bf16 v[104:107], v[140:143], v[198:201], v[104:107]
	v_mfma_f32_16x16x32_bf16 v[92:95], v[128:131], v[202:205], v[92:95]
	v_mfma_f32_16x16x32_bf16 v[92:95], v[132:135], v[206:209], v[92:95]
	v_mfma_f32_16x16x32_bf16 v[88:91], v[136:139], v[202:205], v[88:91]
	v_mfma_f32_16x16x32_bf16 v[88:91], v[140:143], v[206:209], v[88:91]
	v_mfma_f32_16x16x32_bf16 v[76:79], v[128:131], v[210:213], v[76:79]
	v_mfma_f32_16x16x32_bf16 v[76:79], v[132:135], v[214:217], v[76:79]
	v_mfma_f32_16x16x32_bf16 v[72:75], v[136:139], v[210:213], v[72:75]
	v_mfma_f32_16x16x32_bf16 v[72:75], v[140:143], v[214:217], v[72:75]
	s_setprio 0
	s_setprio 1
	v_mfma_f32_16x16x32_bf16 v[116:119], v[144:147], v[186:189], v[116:119]
	v_mfma_f32_16x16x32_bf16 v[116:119], v[148:151], v[190:193], v[116:119]
	v_mfma_f32_16x16x32_bf16 v[112:115], v[178:181], v[186:189], v[112:115]
	v_mfma_f32_16x16x32_bf16 v[112:115], v[182:185], v[190:193], v[112:115]
	v_mfma_f32_16x16x32_bf16 v[100:103], v[144:147], v[194:197], v[100:103]
	v_mfma_f32_16x16x32_bf16 v[100:103], v[148:151], v[198:201], v[100:103]
	v_mfma_f32_16x16x32_bf16 v[96:99], v[178:181], v[194:197], v[96:99]
	v_mfma_f32_16x16x32_bf16 v[96:99], v[182:185], v[198:201], v[96:99]
	v_mfma_f32_16x16x32_bf16 v[84:87], v[144:147], v[202:205], v[84:87]
	v_mfma_f32_16x16x32_bf16 v[84:87], v[148:151], v[206:209], v[84:87]
	v_mfma_f32_16x16x32_bf16 v[80:83], v[178:181], v[202:205], v[80:83]
	v_mfma_f32_16x16x32_bf16 v[80:83], v[182:185], v[206:209], v[80:83]
	v_mfma_f32_16x16x32_bf16 v[68:71], v[144:147], v[210:213], v[68:71]
	v_mfma_f32_16x16x32_bf16 v[68:71], v[148:151], v[214:217], v[68:71]
	v_mfma_f32_16x16x32_bf16 v[64:67], v[178:181], v[210:213], v[64:67]
	v_mfma_f32_16x16x32_bf16 v[64:67], v[182:185], v[214:217], v[64:67]
	s_setprio 0
	s_barrier
	s_add_u32 s42, s40, 0x8000
	s_addc_u32 s43, s41, 0
	s_add_i32 s64, s64, s20
	s_mov_b32 m0, s64
	ds_read_b128 v[186:189], v177 offset:49152
	ds_read_b128 v[190:193], v177 offset:50176
	ds_read_b128 v[194:197], v177 offset:51200
	ds_read_b128 v[198:201], v177 offset:52224
	ds_read_b128 v[202:205], v177 offset:53248
	ds_read_b128 v[206:209], v177 offset:54272
	ds_read_b128 v[210:213], v177 offset:55296
	ds_read_b128 v[214:217], v177 offset:56320
	global_load_lds_dwordx4 v156, s[42:43]
	s_add_i32 m0, s64, 0x2000
	s_add_u32 s40, s40, 0xc000
	v_lshl_add_u64 v[172:173], s[42:43], 0, v[152:153]
	s_addc_u32 s41, s41, 0
	s_add_i32 s42, s65, s20
	global_load_lds_dwordx4 v[172:173], off
	s_mov_b32 m0, s42
	s_nop 0
	global_load_lds_dwordx4 v156, s[40:41]
	s_add_i32 m0, s42, 0x2000
	s_nop 0
	global_load_lds_dwordx4 v152, s[40:41]
	s_mov_b32 m0, s29
	s_nop 0
	global_load_lds_dwordx4 v158, s[38:39]
	s_mov_b32 m0, s30
	s_nop 0
	global_load_lds_dwordx4 v154, s[38:39]
	s_waitcnt vmcnt(8)
	s_waitcnt lgkmcnt(0)
	s_barrier
	s_setprio 1
	s_waitcnt lgkmcnt(0)
	v_mfma_f32_16x16x32_bf16 v[60:63], v[128:131], v[186:189], v[60:63]
	v_mfma_f32_16x16x32_bf16 v[60:63], v[132:135], v[190:193], v[60:63]
	v_mfma_f32_16x16x32_bf16 v[56:59], v[136:139], v[186:189], v[56:59]
	v_mfma_f32_16x16x32_bf16 v[56:59], v[140:143], v[190:193], v[56:59]
	v_mfma_f32_16x16x32_bf16 v[44:47], v[128:131], v[194:197], v[44:47]
	v_mfma_f32_16x16x32_bf16 v[44:47], v[132:135], v[198:201], v[44:47]
	v_mfma_f32_16x16x32_bf16 v[40:43], v[136:139], v[194:197], v[40:43]
	v_mfma_f32_16x16x32_bf16 v[40:43], v[140:143], v[198:201], v[40:43]
	v_mfma_f32_16x16x32_bf16 v[28:31], v[128:131], v[202:205], v[28:31]
	v_mfma_f32_16x16x32_bf16 v[28:31], v[132:135], v[206:209], v[28:31]
	v_mfma_f32_16x16x32_bf16 v[24:27], v[136:139], v[202:205], v[24:27]
	v_mfma_f32_16x16x32_bf16 v[24:27], v[140:143], v[206:209], v[24:27]
	v_mfma_f32_16x16x32_bf16 v[12:15], v[128:131], v[210:213], v[12:15]
	v_mfma_f32_16x16x32_bf16 v[12:15], v[132:135], v[214:217], v[12:15]
	v_mfma_f32_16x16x32_bf16 v[8:11], v[136:139], v[210:213], v[8:11]
	v_mfma_f32_16x16x32_bf16 v[8:11], v[140:143], v[214:217], v[8:11]
	s_setprio 0
	s_setprio 1
	v_mfma_f32_16x16x32_bf16 v[52:55], v[144:147], v[186:189], v[52:55]
	v_mfma_f32_16x16x32_bf16 v[52:55], v[148:151], v[190:193], v[52:55]
	v_mfma_f32_16x16x32_bf16 v[48:51], v[178:181], v[186:189], v[48:51]
	v_mfma_f32_16x16x32_bf16 v[48:51], v[182:185], v[190:193], v[48:51]
	v_mfma_f32_16x16x32_bf16 v[36:39], v[144:147], v[194:197], v[36:39]
	v_mfma_f32_16x16x32_bf16 v[36:39], v[148:151], v[198:201], v[36:39]
	v_mfma_f32_16x16x32_bf16 v[32:35], v[178:181], v[194:197], v[32:35]
	v_mfma_f32_16x16x32_bf16 v[32:35], v[182:185], v[198:201], v[32:35]
	v_mfma_f32_16x16x32_bf16 v[20:23], v[144:147], v[202:205], v[20:23]
	v_mfma_f32_16x16x32_bf16 v[20:23], v[148:151], v[206:209], v[20:23]
	v_mfma_f32_16x16x32_bf16 v[16:19], v[178:181], v[202:205], v[16:19]
	v_mfma_f32_16x16x32_bf16 v[16:19], v[182:185], v[206:209], v[16:19]
	v_mfma_f32_16x16x32_bf16 v[4:7], v[144:147], v[210:213], v[4:7]
	v_mfma_f32_16x16x32_bf16 v[4:7], v[148:151], v[214:217], v[4:7]
	v_mfma_f32_16x16x32_bf16 v[0:3], v[178:181], v[210:213], v[0:3]
	v_mfma_f32_16x16x32_bf16 v[0:3], v[182:185], v[214:217], v[0:3]
	s_setprio 0
	s_barrier
	s_add_u32 s36, s36, 0x10000
	s_addc_u32 s37, s37, 0
	s_add_u32 s78, s78, 0x10000
	s_addc_u32 s82, s82, 0
	s_cmp_ge_u32 s84, s26
	s_mov_b32 s38, s84
	s_cbranch_scc0 .LBB0_193
	s_and_b64 vcc, exec, s[60:61]
	s_cbranch_vccz .LBB0_196
	s_barrier

; #define PG8_STAGE(bufoff, gbase, voff) do { _Pragma("unroll") for (int _i = 0; _i < 2; ++_i) \
;         __builtin_amdgcn_global_load_lds((const unsigned*)((const char*)(gbase) + (voff)[_i]), (PG8_LAS unsigned*)(lds + (bufoff) + ldsw + _i * 8192), 16, 0, 0); } while (0)
; #define PG8_LDA(dst, b, h) do { _Pragma("unroll") for (int m = 0; m < 4; ++m) _Pragma("unroll") for (int k = 0; k < 2; ++k) dst[m][k] = *(const PG8_LAS bf16x8*)(lds + PG8_SA(b, h) + aoff + m * 2048 + k * 1024); } while (0)
; #define PG8_LDB(dst, b, h) do { _Pragma("unroll") for (int n = 0; n < 2; ++n) _Pragma("unroll") for (int k = 0; k < 2; ++k) dst[n][k] = *(const PG8_LAS bf16x8*)(lds + PG8_SB(b, h) + boff + n * 2048 + k * 1024); } while (0)
; #define PG8_WAIT_V(n) asm volatile("s_waitcnt vmcnt(" #n ")" ::: "memory")
; #define PG8_WAIT_L(n) asm volatile("s_waitcnt lgkmcnt(" #n ")" ::: "memory")
; #define PG8_BAR __builtin_amdgcn_s_barrier()
; #define PG8_SCHED __builtin_amdgcn_sched_barrier(0)
; template <class Epi, class Sched, bool ALIGN_EPI = false, bool SP2 = false>
; __device__ __forceinline__ void gemm_phase(PG8_LAS unsigned char* lds, const Gemm g, const Sched& S, const Epi& E) {
;     ...
;         const bool has_next = S.next(ui + 1, nxt);
;         const char* nA = has_next ? (const char*)g.A + (size_t)nxt.pm * tstep : cA; const char* nB = has_next ? (const char*)g.Bt + (size_t)nxt.pn * tstep : cB;
;         for (int t = 0; t < nt; t += 2) {
;             const bool last = (t == nt - 2);
;             const char* a1 = cA + (size_t)(t + 1) * kstepB;
;             const char* a2 = last ? nA : cA + (size_t)(t + 2) * kstepB; const char* b2 = last ? nB : cB + (size_t)(t + 2) * kstepB;
;             const char* a3 = a2 + kstepB; const char* b3 = b2 + kstepB;
;             if (last && has_next) S.a_ready(nxt);
;             if constexpr (SP2) {
;             PG8_LDB(B0, 0, 0); PG8_LDB(B1, 0, 1); PG8_SCHED; PG8_LDA(At, 0, 0); PG8_STAGE(PG8_SA(1, 1), a1 + hstepB, voffA);
;             PG8_WAIT_V(8); PG8_WAIT_L(0); PG8_BAR; PG8_MMA(0, 0, At, B0); PG8_MMA(0, 1, At, B1); PG8_BAR; PG8_SCHED;
;             PG8_LDA(At, 0, 1); PG8_STAGE(PG8_SB(0, 0), b2, voffB); PG8_STAGE(PG8_SB(0, 1), b2 + hstepB, voffB); PG8_STAGE(PG8_SA(0, 0), a2, voffA);
;             PG8_WAIT_V(8); PG8_WAIT_L(0); PG8_BAR; PG8_MMA(1, 0, At, B0); PG8_MMA(1, 1, At, B1); PG8_BAR; PG8_SCHED;
.LBB0_232:
	s_add_u32 s31, s36, 0x4000
	s_addc_u32 s38, s37, 0
	s_cmp_eq_u32 s30, 28
	s_cselect_b32 s42, s26, s31
	s_cselect_b32 s43, s13, s38
	s_cselect_b32 s40, s27, s28
	s_cselect_b32 s41, s11, s29
	s_add_u32 s38, s42, 0x8000
	s_addc_u32 s39, s43, 0
	s_add_i32 s31, 0, 0x10000
	s_add_i32 s60, 0, 0x14000
	v_add_u32_e32 v152, s31, v169
	v_add_u32_e32 v175, s60, v169
	ds_read_b128 v[128:131], v152
	ds_read_b128 v[132:135], v152 offset:1024
	ds_read_b128 v[148:151], v152 offset:2048
	ds_read_b128 v[152:155], v152 offset:3072
	ds_read_b128 v[156:159], v175
	ds_read_b128 v[160:163], v175 offset:1024
	ds_read_b128 v[164:167], v175 offset:2048
	ds_read_b128 v[176:179], v175 offset:3072
	s_add_i32 m0, s17, 0xc000
	ds_read_b128 v[180:183], v174
	ds_read_b128 v[184:187], v174 offset:1024
	ds_read_b128 v[188:191], v174 offset:2048
	ds_read_b128 v[192:195], v174 offset:3072
	ds_read_b128 v[196:199], v174 offset:4096
	ds_read_b128 v[200:203], v174 offset:5120
	ds_read_b128 v[204:207], v174 offset:6144
	ds_read_b128 v[208:211], v174 offset:7168
	global_load_lds_dwordx4 v144, s[36:37]
	s_add_i32 m0, s17, 0xe000
	s_nop 0
	global_load_lds_dwordx4 v146, s[36:37]
	s_waitcnt vmcnt(8)
	s_waitcnt lgkmcnt(0)
	s_barrier
	s_setprio 1
	s_waitcnt lgkmcnt(0)
	v_mfma_f32_16x16x32_bf16 v[124:127], v[128:131], v[180:183], v[124:127]
	v_mfma_f32_16x16x32_bf16 v[124:127], v[132:135], v[184:187], v[124:127]
	v_mfma_f32_16x16x32_bf16 v[120:123], v[148:151], v[180:183], v[120:123]
	v_mfma_f32_16x16x32_bf16 v[120:123], v[152:155], v[184:187], v[120:123]
	v_mfma_f32_16x16x32_bf16 v[108:111], v[128:131], v[188:191], v[108:111]
	v_mfma_f32_16x16x32_bf16 v[108:111], v[132:135], v[192:195], v[108:111]
	v_mfma_f32_16x16x32_bf16 v[104:107], v[148:151], v[188:191], v[104:107]
	v_mfma_f32_16x16x32_bf16 v[104:107], v[152:155], v[192:195], v[104:107]
	v_mfma_f32_16x16x32_bf16 v[92:95], v[128:131], v[196:199], v[92:95]
	v_mfma_f32_16x16x32_bf16 v[92:95], v[132:135], v[200:203], v[92:95]
	v_mfma_f32_16x16x32_bf16 v[88:91], v[148:151], v[196:199], v[88:91]
	v_mfma_f32_16x16x32_bf16 v[88:91], v[152:155], v[200:203], v[88:91]
	v_mfma_f32_16x16x32_bf16 v[76:79], v[128:131], v[204:207], v[76:79]
	v_mfma_f32_16x16x32_bf16 v[76:79], v[132:135], v[208:211], v[76:79]
	v_mfma_f32_16x16x32_bf16 v[72:75], v[148:151], v[204:207], v[72:75]
	v_mfma_f32_16x16x32_bf16 v[72:75], v[152:155], v[208:211], v[72:75]
	s_setprio 0
	s_setprio 1
	v_mfma_f32_16x16x32_bf16 v[116:119], v[156:159], v[180:183], v[116:119]
	v_mfma_f32_16x16x32_bf16 v[116:119], v[160:163], v[184:187], v[116:119]
	v_mfma_f32_16x16x32_bf16 v[112:115], v[164:167], v[180:183], v[112:115]
	v_mfma_f32_16x16x32_bf16 v[112:115], v[176:179], v[184:187], v[112:115]
	v_mfma_f32_16x16x32_bf16 v[100:103], v[156:159], v[188:191], v[100:103]
	v_mfma_f32_16x16x32_bf16 v[100:103], v[160:163], v[192:195], v[100:103]
	v_mfma_f32_16x16x32_bf16 v[96:99], v[164:167], v[188:191], v[96:99]
	v_mfma_f32_16x16x32_bf16 v[96:99], v[176:179], v[192:195], v[96:99]
	v_mfma_f32_16x16x32_bf16 v[84:87], v[156:159], v[196:199], v[84:87]
	v_mfma_f32_16x16x32_bf16 v[84:87], v[160:163], v[200:203], v[84:87]
	v_mfma_f32_16x16x32_bf16 v[80:83], v[164:167], v[196:199], v[80:83]
	v_mfma_f32_16x16x32_bf16 v[80:83], v[176:179], v[200:203], v[80:83]
	v_mfma_f32_16x16x32_bf16 v[68:71], v[156:159], v[204:207], v[68:71]
	v_mfma_f32_16x16x32_bf16 v[68:71], v[160:163], v[208:211], v[68:71]
	v_mfma_f32_16x16x32_bf16 v[64:67], v[164:167], v[204:207], v[64:67]
	v_mfma_f32_16x16x32_bf16 v[64:67], v[176:179], v[208:211], v[64:67]
	s_setprio 0
	s_barrier
	s_add_i32 s31, s31, s14
	s_mov_b32 m0, s31
	ds_read_b128 v[180:183], v174 offset:16384
	ds_read_b128 v[184:187], v174 offset:17408
	ds_read_b128 v[188:191], v174 offset:18432
	ds_read_b128 v[192:195], v174 offset:19456
	ds_read_b128 v[196:199], v174 offset:20480
	ds_read_b128 v[200:203], v174 offset:21504
	ds_read_b128 v[204:207], v174 offset:22528
	ds_read_b128 v[208:211], v174 offset:23552
	global_load_lds_dwordx4 v220, s[40:41]
	s_add_i32 m0, s31, 0x2000
	s_add_u32 s44, s40, 0x4000
	s_addc_u32 s45, s41, 0
	s_add_i32 s31, s60, s14
	global_load_lds_dwordx4 v136, s[40:41]
	s_mov_b32 m0, s31
	s_nop 0
	global_load_lds_dwordx4 v220, s[44:45]
	s_add_i32 m0, s31, 0x2000
	s_nop 0
	global_load_lds_dwordx4 v136, s[44:45]
	s_mov_b32 m0, s17
	s_nop 0
	global_load_lds_dwordx4 v140, s[42:43]
	s_mov_b32 m0, s18
	s_nop 0
	global_load_lds_dwordx4 v138, s[42:43]
	s_waitcnt vmcnt(8)
	s_waitcnt lgkmcnt(0)
	s_barrier
	s_setprio 1
	s_waitcnt lgkmcnt(0)
	v_mfma_f32_16x16x32_bf16 v[60:63], v[128:131], v[180:183], v[60:63]
	v_mfma_f32_16x16x32_bf16 v[60:63], v[132:135], v[184:187], v[60:63]
	v_mfma_f32_16x16x32_bf16 v[56:59], v[148:151], v[180:183], v[56:59]
	v_mfma_f32_16x16x32_bf16 v[56:59], v[152:155], v[184:187], v[56:59]
	v_mfma_f32_16x16x32_bf16 v[48:51], v[128:131], v[188:191], v[48:51]
	v_mfma_f32_16x16x32_bf16 v[48:51], v[132:135], v[192:195], v[48:51]
	v_mfma_f32_16x16x32_bf16 v[40:43], v[148:151], v[188:191], v[40:43]
	v_mfma_f32_16x16x32_bf16 v[40:43], v[152:155], v[192:195], v[40:43]
	v_mfma_f32_16x16x32_bf16 v[32:35], v[128:131], v[196:199], v[32:35]
	v_mfma_f32_16x16x32_bf16 v[32:35], v[132:135], v[200:203], v[32:35]
	v_mfma_f32_16x16x32_bf16 v[24:27], v[148:151], v[196:199], v[24:27]
	v_mfma_f32_16x16x32_bf16 v[24:27], v[152:155], v[200:203], v[24:27]
	v_mfma_f32_16x16x32_bf16 v[16:19], v[128:131], v[204:207], v[16:19]
	v_mfma_f32_16x16x32_bf16 v[16:19], v[132:135], v[208:211], v[16:19]
	v_mfma_f32_16x16x32_bf16 v[8:11], v[148:151], v[204:207], v[8:11]
	v_mfma_f32_16x16x32_bf16 v[8:11], v[152:155], v[208:211], v[8:11]
	s_setprio 0
	s_setprio 1
	v_mfma_f32_16x16x32_bf16 v[52:55], v[156:159], v[180:183], v[52:55]
	v_mfma_f32_16x16x32_bf16 v[52:55], v[160:163], v[184:187], v[52:55]
	v_mfma_f32_16x16x32_bf16 v[44:47], v[164:167], v[180:183], v[44:47]
	v_mfma_f32_16x16x32_bf16 v[44:47], v[176:179], v[184:187], v[44:47]
	v_mfma_f32_16x16x32_bf16 v[36:39], v[156:159], v[188:191], v[36:39]
	v_mfma_f32_16x16x32_bf16 v[36:39], v[160:163], v[192:195], v[36:39]
	v_mfma_f32_16x16x32_bf16 v[28:31], v[164:167], v[188:191], v[28:31]
	v_mfma_f32_16x16x32_bf16 v[28:31], v[176:179], v[192:195], v[28:31]
	v_mfma_f32_16x16x32_bf16 v[20:23], v[156:159], v[196:199], v[20:23]
	v_mfma_f32_16x16x32_bf16 v[20:23], v[160:163], v[200:203], v[20:23]
	v_mfma_f32_16x16x32_bf16 v[12:15], v[164:167], v[196:199], v[12:15]
	v_mfma_f32_16x16x32_bf16 v[12:15], v[176:179], v[200:203], v[12:15]
	v_mfma_f32_16x16x32_bf16 v[4:7], v[156:159], v[204:207], v[4:7]
	v_mfma_f32_16x16x32_bf16 v[4:7], v[160:163], v[208:211], v[4:7]
	v_mfma_f32_16x16x32_bf16 v[0:3], v[164:167], v[204:207], v[0:3]
	v_mfma_f32_16x16x32_bf16 v[0:3], v[176:179], v[208:211], v[0:3]
	s_setprio 0
	s_barrier
; #define PG8_STAGE(bufoff, gbase, voff) do { _Pragma("unroll") for (int _i = 0; _i < 2; ++_i) \
;         __builtin_amdgcn_global_load_lds((const unsigned*)((const char*)(gbase) + (voff)[_i]), (PG8_LAS unsigned*)(lds + (bufoff) + ldsw + _i * 8192), 16, 0, 0); } while (0)
; #define PG8_LDA(dst, b, h) do { _Pragma("unroll") for (int m = 0; m < 4; ++m) _Pragma("unroll") for (int k = 0; k < 2; ++k) dst[m][k] = *(const PG8_LAS bf16x8*)(lds + PG8_SA(b, h) + aoff + m * 2048 + k * 1024); } while (0)
; #define PG8_LDB(dst, b, h) do { _Pragma("unroll") for (int n = 0; n < 2; ++n) _Pragma("unroll") for (int k = 0; k < 2; ++k) dst[n][k] = *(const PG8_LAS bf16x8*)(lds + PG8_SB(b, h) + boff + n * 2048 + k * 1024); } while (0)
; #define PG8_MMA(ai, bj, At, Bt) do { __builtin_amdgcn_s_setprio(1); _Pragma("unroll") for (int m = 0; m < 4; ++m) _Pragma("unroll") for (int n = 0; n < 2; ++n) _Pragma("unroll") for (int k = 0; k < 2; ++k) \
;         acc[ai][bj][m][n] = __builtin_amdgcn_mfma_f32_16x16x32_bf16(Bt[n][k], At[m][k], acc[ai][bj][m][n], 0, 0, 0); __builtin_amdgcn_s_setprio(0); } while (0)
; #define PG8_WAIT_V(n) asm volatile("s_waitcnt vmcnt(" #n ")" ::: "memory")
; #define PG8_WAIT_L(n) asm volatile("s_waitcnt lgkmcnt(" #n ")" ::: "memory")
; #define PG8_BAR __builtin_amdgcn_s_barrier()
; #define PG8_SCHED __builtin_amdgcn_sched_barrier(0)
; template <class Epi, class Sched, bool ALIGN_EPI = false, bool SP2 = false>
; __device__ __forceinline__ void gemm_phase(PG8_LAS unsigned char* lds, const Gemm g, const Sched& S, const Epi& E) {
;     ...
;         for (int t = 0; t < nt; t += 2) {
;     ...
;             PG8_LDB(B0, 1, 0); PG8_LDB(B1, 1, 1); PG8_SCHED; PG8_LDA(At, 1, 0); PG8_STAGE(PG8_SA(0, 1), a2 + hstepB, voffA);
;             PG8_WAIT_V(8); PG8_WAIT_L(0); PG8_BAR; PG8_MMA(0, 0, At, B0); PG8_MMA(0, 1, At, B1); PG8_BAR; PG8_SCHED;
;             PG8_LDA(At, 1, 1); PG8_STAGE(PG8_SB(1, 0), b3, voffB); PG8_STAGE(PG8_SB(1, 1), b3 + hstepB, voffB); PG8_STAGE(PG8_SA(1, 0), a3, voffA);
;             PG8_WAIT_V(8); PG8_WAIT_L(0); PG8_BAR; PG8_MMA(1, 0, At, B0); PG8_MMA(1, 1, At, B1); PG8_BAR; PG8_SCHED;
	s_add_i32 s31, 0, 0x18000
	s_add_i32 s44, 0, 0x1c000
	v_add_u32_e32 v152, s31, v169
	v_add_u32_e32 v175, s44, v169
	ds_read_b128 v[128:131], v152
	ds_read_b128 v[132:135], v152 offset:1024
	ds_read_b128 v[148:151], v152 offset:2048
	ds_read_b128 v[152:155], v152 offset:3072
	ds_read_b128 v[156:159], v175
	ds_read_b128 v[160:163], v175 offset:1024
	ds_read_b128 v[164:167], v175 offset:2048
	ds_read_b128 v[176:179], v175 offset:3072
	s_add_u32 s42, s42, 0x4000
	s_addc_u32 s43, s43, 0
	s_mov_b32 m0, s19
	ds_read_b128 v[180:183], v174 offset:32768
	ds_read_b128 v[184:187], v174 offset:33792
	ds_read_b128 v[188:191], v174 offset:34816
	ds_read_b128 v[192:195], v174 offset:35840
	ds_read_b128 v[196:199], v174 offset:36864
	ds_read_b128 v[200:203], v174 offset:37888
	ds_read_b128 v[204:207], v174 offset:38912
	ds_read_b128 v[208:211], v174 offset:39936
	global_load_lds_dwordx4 v140, s[42:43]
	s_mov_b32 m0, s20
	s_nop 0
	global_load_lds_dwordx4 v138, s[42:43]
	s_waitcnt vmcnt(8)
	s_waitcnt lgkmcnt(0)
	s_barrier
	s_setprio 1
	s_waitcnt lgkmcnt(0)
	v_mfma_f32_16x16x32_bf16 v[124:127], v[128:131], v[180:183], v[124:127]
	v_mfma_f32_16x16x32_bf16 v[124:127], v[132:135], v[184:187], v[124:127]
	v_mfma_f32_16x16x32_bf16 v[120:123], v[148:151], v[180:183], v[120:123]
	v_mfma_f32_16x16x32_bf16 v[120:123], v[152:155], v[184:187], v[120:123]
	v_mfma_f32_16x16x32_bf16 v[108:111], v[128:131], v[188:191], v[108:111]
	v_mfma_f32_16x16x32_bf16 v[108:111], v[132:135], v[192:195], v[108:111]
	v_mfma_f32_16x16x32_bf16 v[104:107], v[148:151], v[188:191], v[104:107]
	v_mfma_f32_16x16x32_bf16 v[104:107], v[152:155], v[192:195], v[104:107]
	v_mfma_f32_16x16x32_bf16 v[92:95], v[128:131], v[196:199], v[92:95]
	v_mfma_f32_16x16x32_bf16 v[92:95], v[132:135], v[200:203], v[92:95]
	v_mfma_f32_16x16x32_bf16 v[88:91], v[148:151], v[196:199], v[88:91]
	v_mfma_f32_16x16x32_bf16 v[88:91], v[152:155], v[200:203], v[88:91]
	v_mfma_f32_16x16x32_bf16 v[76:79], v[128:131], v[204:207], v[76:79]
	v_mfma_f32_16x16x32_bf16 v[76:79], v[132:135], v[208:211], v[76:79]
	v_mfma_f32_16x16x32_bf16 v[72:75], v[148:151], v[204:207], v[72:75]
	v_mfma_f32_16x16x32_bf16 v[72:75], v[152:155], v[208:211], v[72:75]
	s_setprio 0
	s_setprio 1
	v_mfma_f32_16x16x32_bf16 v[116:119], v[156:159], v[180:183], v[116:119]
	v_mfma_f32_16x16x32_bf16 v[116:119], v[160:163], v[184:187], v[116:119]
	v_mfma_f32_16x16x32_bf16 v[112:115], v[164:167], v[180:183], v[112:115]
	v_mfma_f32_16x16x32_bf16 v[112:115], v[176:179], v[184:187], v[112:115]
	v_mfma_f32_16x16x32_bf16 v[100:103], v[156:159], v[188:191], v[100:103]
	v_mfma_f32_16x16x32_bf16 v[100:103], v[160:163], v[192:195], v[100:103]
	v_mfma_f32_16x16x32_bf16 v[96:99], v[164:167], v[188:191], v[96:99]
	v_mfma_f32_16x16x32_bf16 v[96:99], v[176:179], v[192:195], v[96:99]
	v_mfma_f32_16x16x32_bf16 v[84:87], v[156:159], v[196:199], v[84:87]
	v_mfma_f32_16x16x32_bf16 v[84:87], v[160:163], v[200:203], v[84:87]
	v_mfma_f32_16x16x32_bf16 v[80:83], v[164:167], v[196:199], v[80:83]
	v_mfma_f32_16x16x32_bf16 v[80:83], v[176:179], v[200:203], v[80:83]
	v_mfma_f32_16x16x32_bf16 v[68:71], v[156:159], v[204:207], v[68:71]
	v_mfma_f32_16x16x32_bf16 v[68:71], v[160:163], v[208:211], v[68:71]
	v_mfma_f32_16x16x32_bf16 v[64:67], v[164:167], v[204:207], v[64:67]
	v_mfma_f32_16x16x32_bf16 v[64:67], v[176:179], v[208:211], v[64:67]
	s_setprio 0
	s_barrier
	s_add_u32 s42, s40, 0x8000
	s_addc_u32 s43, s41, 0
	s_add_i32 s31, s31, s14
	s_mov_b32 m0, s31
	ds_read_b128 v[180:183], v174 offset:49152
	ds_read_b128 v[184:187], v174 offset:50176
	ds_read_b128 v[188:191], v174 offset:51200
	ds_read_b128 v[192:195], v174 offset:52224
	ds_read_b128 v[196:199], v174 offset:53248
	ds_read_b128 v[200:203], v174 offset:54272
	ds_read_b128 v[204:207], v174 offset:55296
	ds_read_b128 v[208:211], v174 offset:56320
	global_load_lds_dwordx4 v220, s[42:43]
	s_add_i32 m0, s31, 0x2000
	s_add_u32 s40, s40, 0xc000
	s_addc_u32 s41, s41, 0
	s_add_i32 s31, s44, s14
	global_load_lds_dwordx4 v136, s[42:43]
	s_mov_b32 m0, s31
	s_nop 0
	global_load_lds_dwordx4 v220, s[40:41]
	s_add_i32 m0, s31, 0x2000
	s_nop 0
	global_load_lds_dwordx4 v136, s[40:41]
	s_mov_b32 m0, s21
	s_nop 0
	global_load_lds_dwordx4 v140, s[38:39]
	s_mov_b32 m0, s22
	s_nop 0
	global_load_lds_dwordx4 v138, s[38:39]
	s_waitcnt vmcnt(8)
	s_waitcnt lgkmcnt(0)
	s_barrier
	s_setprio 1
	s_waitcnt lgkmcnt(0)
	v_mfma_f32_16x16x32_bf16 v[60:63], v[128:131], v[180:183], v[60:63]
	v_mfma_f32_16x16x32_bf16 v[60:63], v[132:135], v[184:187], v[60:63]
	v_mfma_f32_16x16x32_bf16 v[56:59], v[148:151], v[180:183], v[56:59]
	v_mfma_f32_16x16x32_bf16 v[56:59], v[152:155], v[184:187], v[56:59]
	v_mfma_f32_16x16x32_bf16 v[48:51], v[128:131], v[188:191], v[48:51]
	v_mfma_f32_16x16x32_bf16 v[48:51], v[132:135], v[192:195], v[48:51]
	v_mfma_f32_16x16x32_bf16 v[40:43], v[148:151], v[188:191], v[40:43]
	v_mfma_f32_16x16x32_bf16 v[40:43], v[152:155], v[192:195], v[40:43]
	v_mfma_f32_16x16x32_bf16 v[32:35], v[128:131], v[196:199], v[32:35]
	v_mfma_f32_16x16x32_bf16 v[32:35], v[132:135], v[200:203], v[32:35]
	v_mfma_f32_16x16x32_bf16 v[24:27], v[148:151], v[196:199], v[24:27]
	v_mfma_f32_16x16x32_bf16 v[24:27], v[152:155], v[200:203], v[24:27]
	v_mfma_f32_16x16x32_bf16 v[16:19], v[128:131], v[204:207], v[16:19]
	v_mfma_f32_16x16x32_bf16 v[16:19], v[132:135], v[208:211], v[16:19]
	v_mfma_f32_16x16x32_bf16 v[8:11], v[148:151], v[204:207], v[8:11]
	v_mfma_f32_16x16x32_bf16 v[8:11], v[152:155], v[208:211], v[8:11]
	s_setprio 0
	s_setprio 1
	v_mfma_f32_16x16x32_bf16 v[52:55], v[156:159], v[180:183], v[52:55]
	v_mfma_f32_16x16x32_bf16 v[52:55], v[160:163], v[184:187], v[52:55]
	v_mfma_f32_16x16x32_bf16 v[44:47], v[164:167], v[180:183], v[44:47]
	v_mfma_f32_16x16x32_bf16 v[44:47], v[176:179], v[184:187], v[44:47]
	v_mfma_f32_16x16x32_bf16 v[36:39], v[156:159], v[188:191], v[36:39]
	v_mfma_f32_16x16x32_bf16 v[36:39], v[160:163], v[192:195], v[36:39]
	v_mfma_f32_16x16x32_bf16 v[28:31], v[164:167], v[188:191], v[28:31]
	v_mfma_f32_16x16x32_bf16 v[28:31], v[176:179], v[192:195], v[28:31]
	v_mfma_f32_16x16x32_bf16 v[20:23], v[156:159], v[196:199], v[20:23]
	v_mfma_f32_16x16x32_bf16 v[20:23], v[160:163], v[200:203], v[20:23]
	v_mfma_f32_16x16x32_bf16 v[12:15], v[164:167], v[196:199], v[12:15]
	v_mfma_f32_16x16x32_bf16 v[12:15], v[176:179], v[200:203], v[12:15]
	v_mfma_f32_16x16x32_bf16 v[4:7], v[156:159], v[204:207], v[4:7]
	v_mfma_f32_16x16x32_bf16 v[4:7], v[160:163], v[208:211], v[4:7]
	v_mfma_f32_16x16x32_bf16 v[0:3], v[164:167], v[204:207], v[0:3]
	v_mfma_f32_16x16x32_bf16 v[0:3], v[176:179], v[208:211], v[0:3]
	s_setprio 0
	s_barrier
	s_add_i32 s30, s30, 2
	s_add_u32 s36, s36, 0x10000
	s_addc_u32 s37, s37, 0
	s_add_u32 s28, s28, 0x10000
	s_addc_u32 s29, s29, 0
	s_cmp_gt_u32 s30, 29
	s_cbranch_scc0 .LBB0_232
	s_and_b64 vcc, exec, s[8:9]
	s_cbranch_vccz .LBB0_235
	s_barrier

; #define PG8_STAGE(bufoff, gbase, voff) do { _Pragma("unroll") for (int _i = 0; _i < 2; ++_i) \
;         __builtin_amdgcn_global_load_lds((const unsigned*)((const char*)(gbase) + (voff)[_i]), (PG8_LAS unsigned*)(lds + (bufoff) + ldsw + _i * 8192), 16, 0, 0); } while (0)
; #define PG8_LDA(dst, b, h) do { _Pragma("unroll") for (int m = 0; m < 4; ++m) _Pragma("unroll") for (int k = 0; k < 2; ++k) dst[m][k] = *(const PG8_LAS bf16x8*)(lds + PG8_SA(b, h) + aoff + m * 2048 + k * 1024); } while (0)
; #define PG8_LDB(dst, b, h) do { _Pragma("unroll") for (int n = 0; n < 2; ++n) _Pragma("unroll") for (int k = 0; k < 2; ++k) dst[n][k] = *(const PG8_LAS bf16x8*)(lds + PG8_SB(b, h) + boff + n * 2048 + k * 1024); } while (0)
; #define PG8_MMA(ai, bj, At, Bt) do { __builtin_amdgcn_s_setprio(1); _Pragma("unroll") for (int m = 0; m < 4; ++m) _Pragma("unroll") for (int n = 0; n < 2; ++n) _Pragma("unroll") for (int k = 0; k < 2; ++k) \
;         acc[ai][bj][m][n] = __builtin_amdgcn_mfma_f32_16x16x32_bf16(Bt[n][k], At[m][k], acc[ai][bj][m][n], 0, 0, 0); __builtin_amdgcn_s_setprio(0); } while (0)
; #define PG8_WAIT_V(n) asm volatile("s_waitcnt vmcnt(" #n ")" ::: "memory")
; #define PG8_WAIT_L(n) asm volatile("s_waitcnt lgkmcnt(" #n ")" ::: "memory")
; #define PG8_BAR __builtin_amdgcn_s_barrier()
; #define PG8_SCHED __builtin_amdgcn_sched_barrier(0)
; template <class Epi, class Sched, bool ALIGN_EPI = false, bool SP2 = false>
; __device__ __forceinline__ void gemm_phase(PG8_LAS unsigned char* lds, const Gemm g, const Sched& S, const Epi& E) {
;     ...
;             PG8_LDB(B0, 0, 0); PG8_LDB(B1, 0, 1); PG8_SCHED; PG8_LDA(At, 0, 0); PG8_STAGE(PG8_SA(1, 1), a1 + hstepB, voffA);
;             PG8_WAIT_V(8); PG8_WAIT_L(0); PG8_BAR; PG8_MMA(0, 0, At, B0); PG8_MMA(0, 1, At, B1); PG8_BAR; PG8_SCHED;
;             PG8_LDA(At, 0, 1); PG8_STAGE(PG8_SB(0, 0), b2, voffB); PG8_STAGE(PG8_SB(0, 1), b2 + hstepB, voffB); PG8_STAGE(PG8_SA(0, 0), a2, voffA);
;             PG8_WAIT_V(8); PG8_WAIT_L(0); PG8_BAR; PG8_MMA(1, 0, At, B0); PG8_MMA(1, 1, At, B1); PG8_BAR; PG8_SCHED;
.LBB0_263:
	s_add_u32 s38, s36, 0x4000
	s_addc_u32 s39, s37, 0
	s_cmp_eq_u32 s62, 28
	s_cselect_b32 s42, s30, s38
	s_cselect_b32 s43, s13, s39
	s_cselect_b32 s40, s31, s44
	s_cselect_b32 s41, s11, s45
	s_add_u32 s38, s42, 0x8000
	s_addc_u32 s39, s43, 0
	s_add_i32 s63, 0, 0x10000
	v_add_u32_e32 v151, s63, v165
	s_add_i32 s75, 0, 0x14000
	ds_read_b128 v[128:131], v151
	ds_read_b128 v[132:135], v151 offset:1024
	ds_read_b128 v[152:155], v151 offset:2048
	ds_read_b128 v[156:159], v151 offset:3072
	v_add_u32_e32 v151, s75, v165
	ds_read_b128 v[160:163], v151
	ds_read_b128 v[170:173], v151 offset:1024
	ds_read_b128 v[174:177], v151 offset:2048
	ds_read_b128 v[178:181], v151 offset:3072
	s_add_i32 m0, s19, 0xc000
	ds_read_b128 v[182:185], v168
	ds_read_b128 v[186:189], v168 offset:1024
	ds_read_b128 v[190:193], v168 offset:2048
	ds_read_b128 v[194:197], v168 offset:3072
	ds_read_b128 v[198:201], v168 offset:4096
	ds_read_b128 v[202:205], v168 offset:5120
	ds_read_b128 v[206:209], v168 offset:6144
	ds_read_b128 v[210:213], v168 offset:7168
	global_load_lds_dwordx4 v146, s[36:37]
	s_add_i32 m0, s19, 0xe000
	s_nop 0
	global_load_lds_dwordx4 v148, s[36:37]
	s_waitcnt vmcnt(8)
	s_waitcnt lgkmcnt(0)
	s_barrier
	s_setprio 1
	s_waitcnt lgkmcnt(0)
	v_mfma_f32_16x16x32_bf16 v[124:127], v[128:131], v[182:185], v[124:127]
	v_mfma_f32_16x16x32_bf16 v[124:127], v[132:135], v[186:189], v[124:127]
	v_mfma_f32_16x16x32_bf16 v[116:119], v[152:155], v[182:185], v[116:119]
	v_mfma_f32_16x16x32_bf16 v[116:119], v[156:159], v[186:189], v[116:119]
	v_mfma_f32_16x16x32_bf16 v[108:111], v[128:131], v[190:193], v[108:111]
	v_mfma_f32_16x16x32_bf16 v[108:111], v[132:135], v[194:197], v[108:111]
	v_mfma_f32_16x16x32_bf16 v[100:103], v[152:155], v[190:193], v[100:103]
	v_mfma_f32_16x16x32_bf16 v[100:103], v[156:159], v[194:197], v[100:103]
	v_mfma_f32_16x16x32_bf16 v[92:95], v[128:131], v[198:201], v[92:95]
	v_mfma_f32_16x16x32_bf16 v[92:95], v[132:135], v[202:205], v[92:95]
	v_mfma_f32_16x16x32_bf16 v[84:87], v[152:155], v[198:201], v[84:87]
	v_mfma_f32_16x16x32_bf16 v[84:87], v[156:159], v[202:205], v[84:87]
	v_mfma_f32_16x16x32_bf16 v[76:79], v[128:131], v[206:209], v[76:79]
	v_mfma_f32_16x16x32_bf16 v[76:79], v[132:135], v[210:213], v[76:79]
	v_mfma_f32_16x16x32_bf16 v[68:71], v[152:155], v[206:209], v[68:71]
	v_mfma_f32_16x16x32_bf16 v[68:71], v[156:159], v[210:213], v[68:71]
	s_setprio 0
	s_setprio 1
	v_mfma_f32_16x16x32_bf16 v[120:123], v[160:163], v[182:185], v[120:123]
	v_mfma_f32_16x16x32_bf16 v[120:123], v[170:173], v[186:189], v[120:123]
	v_mfma_f32_16x16x32_bf16 v[112:115], v[174:177], v[182:185], v[112:115]
	v_mfma_f32_16x16x32_bf16 v[112:115], v[178:181], v[186:189], v[112:115]
	v_mfma_f32_16x16x32_bf16 v[104:107], v[160:163], v[190:193], v[104:107]
	v_mfma_f32_16x16x32_bf16 v[104:107], v[170:173], v[194:197], v[104:107]
	v_mfma_f32_16x16x32_bf16 v[96:99], v[174:177], v[190:193], v[96:99]
	v_mfma_f32_16x16x32_bf16 v[96:99], v[178:181], v[194:197], v[96:99]
	v_mfma_f32_16x16x32_bf16 v[88:91], v[160:163], v[198:201], v[88:91]
	v_mfma_f32_16x16x32_bf16 v[88:91], v[170:173], v[202:205], v[88:91]
	v_mfma_f32_16x16x32_bf16 v[80:83], v[174:177], v[198:201], v[80:83]
	v_mfma_f32_16x16x32_bf16 v[80:83], v[178:181], v[202:205], v[80:83]
	v_mfma_f32_16x16x32_bf16 v[72:75], v[160:163], v[206:209], v[72:75]
	v_mfma_f32_16x16x32_bf16 v[72:75], v[170:173], v[210:213], v[72:75]
	v_mfma_f32_16x16x32_bf16 v[64:67], v[174:177], v[206:209], v[64:67]
	v_mfma_f32_16x16x32_bf16 v[64:67], v[178:181], v[210:213], v[64:67]
	s_setprio 0
	s_barrier
	s_add_i32 s63, s63, s16
	s_mov_b32 m0, s63
	ds_read_b128 v[182:185], v168 offset:16384
	ds_read_b128 v[186:189], v168 offset:17408
	ds_read_b128 v[190:193], v168 offset:18432
	ds_read_b128 v[194:197], v168 offset:19456
	ds_read_b128 v[198:201], v168 offset:20480
	ds_read_b128 v[202:205], v168 offset:21504
	ds_read_b128 v[206:209], v168 offset:22528
	ds_read_b128 v[210:213], v168 offset:23552
	global_load_lds_dwordx4 v140, s[40:41]
	s_add_i32 m0, s63, 0x2000
	s_add_u32 s66, s40, 0x4000
	s_addc_u32 s67, s41, 0
	s_add_i32 s63, s75, s16
	global_load_lds_dwordx4 v136, s[40:41]
	s_mov_b32 m0, s63
	s_nop 0
	global_load_lds_dwordx4 v140, s[66:67]
	s_add_i32 m0, s63, 0x2000
	s_nop 0
	global_load_lds_dwordx4 v136, s[66:67]
	s_mov_b32 m0, s19
	s_nop 0
	global_load_lds_dwordx4 v142, s[42:43]
	s_mov_b32 m0, s20
	s_nop 0
	global_load_lds_dwordx4 v138, s[42:43]
	s_waitcnt vmcnt(8)
	s_waitcnt lgkmcnt(0)
	s_barrier
	s_setprio 1
	s_waitcnt lgkmcnt(0)
	v_mfma_f32_16x16x32_bf16 v[60:63], v[128:131], v[182:185], v[60:63]
	v_mfma_f32_16x16x32_bf16 v[60:63], v[132:135], v[186:189], v[60:63]
	v_mfma_f32_16x16x32_bf16 v[52:55], v[152:155], v[182:185], v[52:55]
	v_mfma_f32_16x16x32_bf16 v[52:55], v[156:159], v[186:189], v[52:55]
	v_mfma_f32_16x16x32_bf16 v[44:47], v[128:131], v[190:193], v[44:47]
	v_mfma_f32_16x16x32_bf16 v[44:47], v[132:135], v[194:197], v[44:47]
	v_mfma_f32_16x16x32_bf16 v[36:39], v[152:155], v[190:193], v[36:39]
	v_mfma_f32_16x16x32_bf16 v[36:39], v[156:159], v[194:197], v[36:39]
	v_mfma_f32_16x16x32_bf16 v[28:31], v[128:131], v[198:201], v[28:31]
	v_mfma_f32_16x16x32_bf16 v[28:31], v[132:135], v[202:205], v[28:31]
	v_mfma_f32_16x16x32_bf16 v[20:23], v[152:155], v[198:201], v[20:23]
	v_mfma_f32_16x16x32_bf16 v[20:23], v[156:159], v[202:205], v[20:23]
	v_mfma_f32_16x16x32_bf16 v[12:15], v[128:131], v[206:209], v[12:15]
	v_mfma_f32_16x16x32_bf16 v[12:15], v[132:135], v[210:213], v[12:15]
	v_mfma_f32_16x16x32_bf16 v[4:7], v[152:155], v[206:209], v[4:7]
	v_mfma_f32_16x16x32_bf16 v[4:7], v[156:159], v[210:213], v[4:7]
	s_setprio 0
	s_setprio 1
	v_mfma_f32_16x16x32_bf16 v[56:59], v[160:163], v[182:185], v[56:59]
	v_mfma_f32_16x16x32_bf16 v[56:59], v[170:173], v[186:189], v[56:59]
	v_mfma_f32_16x16x32_bf16 v[48:51], v[174:177], v[182:185], v[48:51]
	v_mfma_f32_16x16x32_bf16 v[48:51], v[178:181], v[186:189], v[48:51]
	v_mfma_f32_16x16x32_bf16 v[40:43], v[160:163], v[190:193], v[40:43]
	v_mfma_f32_16x16x32_bf16 v[40:43], v[170:173], v[194:197], v[40:43]
	v_mfma_f32_16x16x32_bf16 v[32:35], v[174:177], v[190:193], v[32:35]
	v_mfma_f32_16x16x32_bf16 v[32:35], v[178:181], v[194:197], v[32:35]
	v_mfma_f32_16x16x32_bf16 v[24:27], v[160:163], v[198:201], v[24:27]
	v_mfma_f32_16x16x32_bf16 v[24:27], v[170:173], v[202:205], v[24:27]
	v_mfma_f32_16x16x32_bf16 v[16:19], v[174:177], v[198:201], v[16:19]
	v_mfma_f32_16x16x32_bf16 v[16:19], v[178:181], v[202:205], v[16:19]
	v_mfma_f32_16x16x32_bf16 v[8:11], v[160:163], v[206:209], v[8:11]
	v_mfma_f32_16x16x32_bf16 v[8:11], v[170:173], v[210:213], v[8:11]
	v_mfma_f32_16x16x32_bf16 v[0:3], v[174:177], v[206:209], v[0:3]
	v_mfma_f32_16x16x32_bf16 v[0:3], v[178:181], v[210:213], v[0:3]
	s_setprio 0
	s_barrier
; #define PG8_STAGE(bufoff, gbase, voff) do { _Pragma("unroll") for (int _i = 0; _i < 2; ++_i) \
;         __builtin_amdgcn_global_load_lds((const unsigned*)((const char*)(gbase) + (voff)[_i]), (PG8_LAS unsigned*)(lds + (bufoff) + ldsw + _i * 8192), 16, 0, 0); } while (0)
; #define PG8_LDA(dst, b, h) do { _Pragma("unroll") for (int m = 0; m < 4; ++m) _Pragma("unroll") for (int k = 0; k < 2; ++k) dst[m][k] = *(const PG8_LAS bf16x8*)(lds + PG8_SA(b, h) + aoff + m * 2048 + k * 1024); } while (0)
; #define PG8_LDB(dst, b, h) do { _Pragma("unroll") for (int n = 0; n < 2; ++n) _Pragma("unroll") for (int k = 0; k < 2; ++k) dst[n][k] = *(const PG8_LAS bf16x8*)(lds + PG8_SB(b, h) + boff + n * 2048 + k * 1024); } while (0)
; #define PG8_MMA(ai, bj, At, Bt) do { __builtin_amdgcn_s_setprio(1); _Pragma("unroll") for (int m = 0; m < 4; ++m) _Pragma("unroll") for (int n = 0; n < 2; ++n) _Pragma("unroll") for (int k = 0; k < 2; ++k) \
;         acc[ai][bj][m][n] = __builtin_amdgcn_mfma_f32_16x16x32_bf16(Bt[n][k], At[m][k], acc[ai][bj][m][n], 0, 0, 0); __builtin_amdgcn_s_setprio(0); } while (0)
; #define PG8_WAIT_V(n) asm volatile("s_waitcnt vmcnt(" #n ")" ::: "memory")
; #define PG8_WAIT_L(n) asm volatile("s_waitcnt lgkmcnt(" #n ")" ::: "memory")
; #define PG8_BAR __builtin_amdgcn_s_barrier()
; #define PG8_SCHED __builtin_amdgcn_sched_barrier(0)
; template <class Epi, class Sched, bool ALIGN_EPI = false, bool SP2 = false>
; __device__ __forceinline__ void gemm_phase(PG8_LAS unsigned char* lds, const Gemm g, const Sched& S, const Epi& E) {
;     ...
;             PG8_LDB(B0, 1, 0); PG8_LDB(B1, 1, 1); PG8_SCHED; PG8_LDA(At, 1, 0); PG8_STAGE(PG8_SA(0, 1), a2 + hstepB, voffA);
;             PG8_WAIT_V(8); PG8_WAIT_L(0); PG8_BAR; PG8_MMA(0, 0, At, B0); PG8_MMA(0, 1, At, B1); PG8_BAR; PG8_SCHED;
;             PG8_LDA(At, 1, 1); PG8_STAGE(PG8_SB(1, 0), b3, voffB); PG8_STAGE(PG8_SB(1, 1), b3 + hstepB, voffB); PG8_STAGE(PG8_SA(1, 0), a3, voffA);
;             PG8_WAIT_V(8); PG8_WAIT_L(0); PG8_BAR; PG8_MMA(1, 0, At, B0); PG8_MMA(1, 1, At, B1); PG8_BAR; PG8_SCHED;
	s_add_i32 s63, 0, 0x18000
	v_add_u32_e32 v151, s63, v165
	s_add_i32 s66, 0, 0x1c000
	ds_read_b128 v[128:131], v151
	ds_read_b128 v[132:135], v151 offset:1024
	ds_read_b128 v[152:155], v151 offset:2048
	ds_read_b128 v[156:159], v151 offset:3072
	v_add_u32_e32 v151, s66, v165
	ds_read_b128 v[160:163], v151
	ds_read_b128 v[170:173], v151 offset:1024
	ds_read_b128 v[174:177], v151 offset:2048
	ds_read_b128 v[178:181], v151 offset:3072
	s_add_u32 s42, s42, 0x4000
	s_addc_u32 s43, s43, 0
	s_mov_b32 m0, s21
	ds_read_b128 v[182:185], v168 offset:32768
	ds_read_b128 v[186:189], v168 offset:33792
	ds_read_b128 v[190:193], v168 offset:34816
	ds_read_b128 v[194:197], v168 offset:35840
	ds_read_b128 v[198:201], v168 offset:36864
	ds_read_b128 v[202:205], v168 offset:37888
	ds_read_b128 v[206:209], v168 offset:38912
	ds_read_b128 v[210:213], v168 offset:39936
	global_load_lds_dwordx4 v142, s[42:43]
	s_mov_b32 m0, s22
	s_nop 0
	global_load_lds_dwordx4 v138, s[42:43]
	s_waitcnt vmcnt(8)
	s_waitcnt lgkmcnt(0)
	s_barrier
	s_setprio 1
	s_waitcnt lgkmcnt(0)
	v_mfma_f32_16x16x32_bf16 v[124:127], v[128:131], v[182:185], v[124:127]
	v_mfma_f32_16x16x32_bf16 v[124:127], v[132:135], v[186:189], v[124:127]
	v_mfma_f32_16x16x32_bf16 v[116:119], v[152:155], v[182:185], v[116:119]
	v_mfma_f32_16x16x32_bf16 v[116:119], v[156:159], v[186:189], v[116:119]
	v_mfma_f32_16x16x32_bf16 v[108:111], v[128:131], v[190:193], v[108:111]
	v_mfma_f32_16x16x32_bf16 v[108:111], v[132:135], v[194:197], v[108:111]
	v_mfma_f32_16x16x32_bf16 v[100:103], v[152:155], v[190:193], v[100:103]
	v_mfma_f32_16x16x32_bf16 v[100:103], v[156:159], v[194:197], v[100:103]
	v_mfma_f32_16x16x32_bf16 v[92:95], v[128:131], v[198:201], v[92:95]
	v_mfma_f32_16x16x32_bf16 v[92:95], v[132:135], v[202:205], v[92:95]
	v_mfma_f32_16x16x32_bf16 v[84:87], v[152:155], v[198:201], v[84:87]
	v_mfma_f32_16x16x32_bf16 v[84:87], v[156:159], v[202:205], v[84:87]
	v_mfma_f32_16x16x32_bf16 v[76:79], v[128:131], v[206:209], v[76:79]
	v_mfma_f32_16x16x32_bf16 v[76:79], v[132:135], v[210:213], v[76:79]
	v_mfma_f32_16x16x32_bf16 v[68:71], v[152:155], v[206:209], v[68:71]
	v_mfma_f32_16x16x32_bf16 v[68:71], v[156:159], v[210:213], v[68:71]
	s_setprio 0
	s_setprio 1
	v_mfma_f32_16x16x32_bf16 v[120:123], v[160:163], v[182:185], v[120:123]
	v_mfma_f32_16x16x32_bf16 v[120:123], v[170:173], v[186:189], v[120:123]
	v_mfma_f32_16x16x32_bf16 v[112:115], v[174:177], v[182:185], v[112:115]
	v_mfma_f32_16x16x32_bf16 v[112:115], v[178:181], v[186:189], v[112:115]
	v_mfma_f32_16x16x32_bf16 v[104:107], v[160:163], v[190:193], v[104:107]
	v_mfma_f32_16x16x32_bf16 v[104:107], v[170:173], v[194:197], v[104:107]
	v_mfma_f32_16x16x32_bf16 v[96:99], v[174:177], v[190:193], v[96:99]
	v_mfma_f32_16x16x32_bf16 v[96:99], v[178:181], v[194:197], v[96:99]
	v_mfma_f32_16x16x32_bf16 v[88:91], v[160:163], v[198:201], v[88:91]
	v_mfma_f32_16x16x32_bf16 v[88:91], v[170:173], v[202:205], v[88:91]
	v_mfma_f32_16x16x32_bf16 v[80:83], v[174:177], v[198:201], v[80:83]
	v_mfma_f32_16x16x32_bf16 v[80:83], v[178:181], v[202:205], v[80:83]
	v_mfma_f32_16x16x32_bf16 v[72:75], v[160:163], v[206:209], v[72:75]
	v_mfma_f32_16x16x32_bf16 v[72:75], v[170:173], v[210:213], v[72:75]
	v_mfma_f32_16x16x32_bf16 v[64:67], v[174:177], v[206:209], v[64:67]
	v_mfma_f32_16x16x32_bf16 v[64:67], v[178:181], v[210:213], v[64:67]
	s_setprio 0
	s_barrier
	s_add_u32 s42, s40, 0x8000
	s_addc_u32 s43, s41, 0
	s_add_i32 s63, s63, s16
	s_mov_b32 m0, s63
	ds_read_b128 v[182:185], v168 offset:49152
	ds_read_b128 v[186:189], v168 offset:50176
	ds_read_b128 v[190:193], v168 offset:51200
	ds_read_b128 v[194:197], v168 offset:52224
	ds_read_b128 v[198:201], v168 offset:53248
	ds_read_b128 v[202:205], v168 offset:54272
	ds_read_b128 v[206:209], v168 offset:55296
	ds_read_b128 v[210:213], v168 offset:56320
	global_load_lds_dwordx4 v140, s[42:43]
	s_add_i32 m0, s63, 0x2000
	s_add_u32 s40, s40, 0xc000
	v_lshl_add_u64 v[214:215], s[42:43], 0, v[136:137]
	s_addc_u32 s41, s41, 0
	s_add_i32 s42, s66, s16
	global_load_lds_dwordx4 v[214:215], off
	s_mov_b32 m0, s42
	s_nop 0
	global_load_lds_dwordx4 v140, s[40:41]
	s_add_i32 m0, s42, 0x2000
	s_nop 0
	global_load_lds_dwordx4 v136, s[40:41]
	s_mov_b32 m0, s25
	s_nop 0
	global_load_lds_dwordx4 v142, s[38:39]
	s_mov_b32 m0, s26
	s_nop 0
	global_load_lds_dwordx4 v138, s[38:39]
	s_waitcnt vmcnt(8)
	s_waitcnt lgkmcnt(0)
	s_barrier
	s_setprio 1
	s_waitcnt lgkmcnt(0)
	v_mfma_f32_16x16x32_bf16 v[60:63], v[128:131], v[182:185], v[60:63]
	v_mfma_f32_16x16x32_bf16 v[60:63], v[132:135], v[186:189], v[60:63]
	v_mfma_f32_16x16x32_bf16 v[52:55], v[152:155], v[182:185], v[52:55]
	v_mfma_f32_16x16x32_bf16 v[52:55], v[156:159], v[186:189], v[52:55]
	v_mfma_f32_16x16x32_bf16 v[44:47], v[128:131], v[190:193], v[44:47]
	v_mfma_f32_16x16x32_bf16 v[44:47], v[132:135], v[194:197], v[44:47]
	v_mfma_f32_16x16x32_bf16 v[36:39], v[152:155], v[190:193], v[36:39]
	v_mfma_f32_16x16x32_bf16 v[36:39], v[156:159], v[194:197], v[36:39]
	v_mfma_f32_16x16x32_bf16 v[28:31], v[128:131], v[198:201], v[28:31]
	v_mfma_f32_16x16x32_bf16 v[28:31], v[132:135], v[202:205], v[28:31]
	v_mfma_f32_16x16x32_bf16 v[20:23], v[152:155], v[198:201], v[20:23]
	v_mfma_f32_16x16x32_bf16 v[20:23], v[156:159], v[202:205], v[20:23]
	v_mfma_f32_16x16x32_bf16 v[12:15], v[128:131], v[206:209], v[12:15]
	v_mfma_f32_16x16x32_bf16 v[12:15], v[132:135], v[210:213], v[12:15]
	v_mfma_f32_16x16x32_bf16 v[4:7], v[152:155], v[206:209], v[4:7]
	v_mfma_f32_16x16x32_bf16 v[4:7], v[156:159], v[210:213], v[4:7]
	s_setprio 0
	s_setprio 1
	v_mfma_f32_16x16x32_bf16 v[56:59], v[160:163], v[182:185], v[56:59]
	v_mfma_f32_16x16x32_bf16 v[56:59], v[170:173], v[186:189], v[56:59]
	v_mfma_f32_16x16x32_bf16 v[48:51], v[174:177], v[182:185], v[48:51]
	v_mfma_f32_16x16x32_bf16 v[48:51], v[178:181], v[186:189], v[48:51]
	v_mfma_f32_16x16x32_bf16 v[40:43], v[160:163], v[190:193], v[40:43]
	v_mfma_f32_16x16x32_bf16 v[40:43], v[170:173], v[194:197], v[40:43]
	v_mfma_f32_16x16x32_bf16 v[32:35], v[174:177], v[190:193], v[32:35]
	v_mfma_f32_16x16x32_bf16 v[32:35], v[178:181], v[194:197], v[32:35]
	v_mfma_f32_16x16x32_bf16 v[24:27], v[160:163], v[198:201], v[24:27]
	v_mfma_f32_16x16x32_bf16 v[24:27], v[170:173], v[202:205], v[24:27]
	v_mfma_f32_16x16x32_bf16 v[16:19], v[174:177], v[198:201], v[16:19]
	v_mfma_f32_16x16x32_bf16 v[16:19], v[178:181], v[202:205], v[16:19]
	v_mfma_f32_16x16x32_bf16 v[8:11], v[160:163], v[206:209], v[8:11]
	v_mfma_f32_16x16x32_bf16 v[8:11], v[170:173], v[210:213], v[8:11]
	v_mfma_f32_16x16x32_bf16 v[0:3], v[174:177], v[206:209], v[0:3]
	v_mfma_f32_16x16x32_bf16 v[0:3], v[178:181], v[210:213], v[0:3]
	s_setprio 0
	s_barrier
	s_add_i32 s62, s62, 2
	s_add_u32 s36, s36, 0x10000
	s_addc_u32 s37, s37, 0
	s_add_u32 s44, s44, 0x10000
	s_addc_u32 s45, s45, 0
	s_cmp_gt_u32 s62, 29
	s_cbranch_scc0 .LBB0_263
	s_and_b64 vcc, exec, s[8:9]
	s_cbranch_vccz .LBB0_266
	s_barrier
